# pooling residual rows of all latent rows moved beside the GLA chain in both layers; mix phase pools only context rows
# baseline (speedup 1.0000x reference)
; __device__ __forceinline__ int opaque_tid() { int t = threadIdx.x; asm volatile("" : "+v"(t)); return t; }
; __device__ __forceinline__ void mix_resid_rows(const Params& p, int nr, int wg0, int nwg) {
;     const int tid_ = opaque_tid(), lane = tid_ & 63, wave = tid_ >> 6;
;     const bf16_t* pu = (const bf16_t*)(p.ws + OFF_C + C_PU); bf16_t* mixed = (bf16_t*)(p.ws + OFF_H);
;     for (int r = ((int)blockIdx.x - wg0) * 8 + wave; r < nr; r += nwg * 8) {
;         int t, seg0, seg1, r0;
;         if (r < ROWS_LAT) { t = r & (T - 1); r0 = r - t; seg0 = t & ~63; seg1 = seg0 + 63; } else { t = (r - ROWS_LAT) & (CTXL - 1); r0 = r - t; seg0 = 0; seg1 = CTXL - 1; }
;         u32x4 pw0[4], pw1[16], uc[2];
; #pragma unroll
;         for (int k = 0; k < 4; ++k) { const int tc = min(max(t - 2 + k, seg0), seg1); pw0[k] = *(const u32x4*)(pu + (size_t)(r0 + tc) * 1024 + lane * 8); }
; #pragma unroll
;         for (int k = 0; k < 16; ++k) { const int tc = min(max(t - 8 + k, seg0), seg1); pw1[k] = *(const u32x4*)(pu + (size_t)(r0 + tc) * 1024 + 512 + lane * 8); }
; #pragma unroll
;         for (int it = 0; it < 2; ++it) uc[it] = *(const u32x4*)(pu + (size_t)r * 1024 + it * 512 + lane * 8);
.LBB0_536:
	v_mov_b32_e32 v0, v194
	v_readlane_b32 s1, v239, 44
	v_ashrrev_i32_e32 v1, 6, v0
	s_nop 0
	v_add_u32_e32 v86, s1, v1
	s_movk_i32 s1, 0x4000
	v_cmp_gt_i32_e32 vcc, s1, v86
	s_and_saveexec_b64 s[2:3], vcc
	s_waitcnt lgkmcnt(0)
	v_readlane_b32 s12, v239, 58
	v_readlane_b32 s13, v239, 59
	s_cbranch_execz .LBB0_540
	v_lshlrev_b32_e32 v1, 3, v0
	v_and_b32_e32 v4, 0x1f8, v1
	v_bfe_u32 v1, v1, 8, 1
	v_lshlrev_b32_e64 v94, v1, 1
	v_or_b32_e32 v1, 0x200, v4
	v_lshlrev_b32_e32 v64, 1, v4
	v_lshrrev_b32_e32 v1, 8, v1
	v_and_b32_e32 v0, 63, v0
	v_ashrrev_i32_e32 v87, 31, v86
	v_lshl_add_u64 v[2:3], s[10:11], 0, v[64:65]
	v_lshlrev_b32_e64 v95, v1, 1
	v_lshlrev_b32_e32 v64, 4, v0
	v_lshlrev_b64 v[0:1], 12, v[86:87]
	s_mov_b64 s[8:9], 0x19afc000
	v_lshl_add_u64 v[90:91], s[10:11], 0, v[0:1]
	v_lshlrev_b64 v[0:1], 11, v[86:87]
	v_lshl_add_u64 v[88:89], v[2:3], 0, s[8:9]
	v_lshl_add_u64 v[92:93], s[10:11], 0, v[0:1]
	s_mov_b64 s[10:11], 0
.LBB0_539:
	v_and_b32_e32 v87, 0xfff, v86
	v_and_b32_e32 v105, 0xfc0, v86
	v_add_u32_e32 v107, -8, v87
	v_or_b32_e32 v106, 63, v105
	v_max_i32_e32 v8, v107, v105
	v_and_b32_e32 v20, 0xfffff000, v86
	v_min_i32_e32 v8, v8, v106
	v_or_b32_e32 v8, v8, v20
	v_ashrrev_i32_e32 v9, 31, v8
	v_lshlrev_b64 v[8:9], 11, v[8:9]
	v_lshl_add_u64 v[8:9], v[88:89], 0, v[8:9]
	v_add_u32_e32 v108, -7, v87
	global_load_dwordx4 v[40:43], v[8:9], off offset:1024
	v_max_i32_e32 v8, v108, v105
	v_min_i32_e32 v8, v8, v106
	v_or_b32_e32 v8, v8, v20
	v_ashrrev_i32_e32 v9, 31, v8
	v_lshlrev_b64 v[8:9], 11, v[8:9]
	v_lshl_add_u64 v[8:9], v[88:89], 0, v[8:9]
	v_add_u32_e32 v109, -6, v87
	v_add_u32_e32 v104, -2, v87
	global_load_dwordx4 v[44:47], v[8:9], off offset:1024
	v_max_i32_e32 v8, v109, v105
	v_max_i32_e32 v0, v104, v105
	v_min_i32_e32 v8, v8, v106
	v_min_i32_e32 v0, v0, v106
	v_or_b32_e32 v8, v8, v20
	v_or_b32_e32 v0, v0, v20
	v_ashrrev_i32_e32 v9, 31, v8
	v_ashrrev_i32_e32 v1, 31, v0
	v_add_u32_e32 v97, -1, v87
	v_lshlrev_b64 v[8:9], 11, v[8:9]
	v_lshlrev_b64 v[0:1], 11, v[0:1]
	v_max_i32_e32 v2, v97, v105
	v_lshl_add_u64 v[8:9], v[88:89], 0, v[8:9]
	v_add_u32_e32 v110, -5, v87
	v_lshl_add_u64 v[0:1], v[88:89], 0, v[0:1]
	v_min_i32_e32 v2, v2, v106
	global_load_dwordx4 v[48:51], v[8:9], off offset:1024
	v_max_i32_e32 v8, v110, v105
	global_load_dwordx4 v[70:73], v[0:1], off
	v_or_b32_e32 v2, v2, v20
	v_min_u32_e32 v4, v87, v106
	v_min_i32_e32 v8, v8, v106
	v_ashrrev_i32_e32 v3, 31, v2
	v_or_b32_e32 v4, v4, v20
	v_or_b32_e32 v8, v8, v20
	v_lshlrev_b64 v[2:3], 11, v[2:3]
	v_ashrrev_i32_e32 v5, 31, v4
	v_ashrrev_i32_e32 v9, 31, v8
	v_lshl_add_u64 v[2:3], v[88:89], 0, v[2:3]
	v_lshlrev_b64 v[4:5], 11, v[4:5]
	v_lshlrev_b64 v[8:9], 11, v[8:9]
	global_load_dwordx4 v[74:77], v[2:3], off
	v_lshl_add_u64 v[4:5], v[88:89], 0, v[4:5]
	v_add_u32_e32 v96, 1, v87
	v_lshl_add_u64 v[8:9], v[88:89], 0, v[8:9]
	v_add_u32_e32 v111, -4, v87
	global_load_dwordx4 v[78:81], v[4:5], off
	v_max_u32_e32 v6, v96, v105
	global_load_dwordx4 v[52:55], v[8:9], off offset:1024
	v_max_i32_e32 v8, v111, v105
	v_min_u32_e32 v6, v6, v106
	v_min_i32_e32 v8, v8, v106
	v_or_b32_e32 v6, v6, v20
	v_or_b32_e32 v8, v8, v20
	v_ashrrev_i32_e32 v7, 31, v6
	v_ashrrev_i32_e32 v9, 31, v8
	v_lshlrev_b64 v[6:7], 11, v[6:7]
	v_lshlrev_b64 v[8:9], 11, v[8:9]
	v_lshl_add_u64 v[6:7], v[88:89], 0, v[6:7]
	v_lshl_add_u64 v[8:9], v[88:89], 0, v[8:9]
	v_add_u32_e32 v112, -3, v87
	global_load_dwordx4 v[82:85], v[6:7], off
	global_load_dwordx4 v[56:59], v[8:9], off offset:1024
	v_max_i32_e32 v8, v112, v105
	v_min_i32_e32 v8, v8, v106
	v_or_b32_e32 v8, v8, v20
	v_ashrrev_i32_e32 v9, 31, v8
	v_lshlrev_b64 v[8:9], 11, v[8:9]
	v_lshl_add_u64 v[8:9], v[88:89], 0, v[8:9]
	v_add_u32_e32 v98, 2, v87
	v_add_u32_e32 v99, 3, v87
	v_add_u32_e32 v100, 4, v87
	v_add_u32_e32 v101, 5, v87
	v_add_u32_e32 v102, 6, v87
	v_add_u32_e32 v103, 7, v87
	global_load_dwordx4 v[60:63], v[8:9], off offset:1024
	global_load_dwordx4 v[36:39], v[0:1], off offset:1024
	global_load_dwordx4 v[32:35], v[2:3], off offset:1024
	global_load_dwordx4 v[28:31], v[4:5], off offset:1024
	global_load_dwordx4 v[24:27], v[6:7], off offset:1024
	v_max_u32_e32 v0, v98, v105
	v_max_u32_e32 v4, v99, v105
	v_max_u32_e32 v8, v100, v105
	v_max_u32_e32 v12, v101, v105
	v_max_u32_e32 v16, v102, v105
	v_max_u32_e32 v21, v103, v105
	v_min_u32_e32 v0, v0, v106
	v_min_u32_e32 v4, v4, v106
	v_min_u32_e32 v8, v8, v106
	v_min_u32_e32 v12, v12, v106
	v_min_u32_e32 v16, v16, v106
	v_min_u32_e32 v21, v21, v106
	v_or_b32_e32 v0, v0, v20
	v_or_b32_e32 v4, v4, v20
	v_or_b32_e32 v8, v8, v20
	v_or_b32_e32 v12, v12, v20
	v_or_b32_e32 v16, v16, v20
	v_or_b32_e32 v20, v21, v20
	v_ashrrev_i32_e32 v1, 31, v0
	v_ashrrev_i32_e32 v5, 31, v4
	v_ashrrev_i32_e32 v9, 31, v8
	v_ashrrev_i32_e32 v13, 31, v12
	v_ashrrev_i32_e32 v17, 31, v16
	v_ashrrev_i32_e32 v21, 31, v20
	v_lshl_add_u64 v[66:67], v[92:93], 0, v[64:65]
	s_mov_b32 s1, 0x19afc000
	v_lshlrev_b64 v[0:1], 11, v[0:1]
	v_lshlrev_b64 v[4:5], 11, v[4:5]
	v_lshlrev_b64 v[8:9], 11, v[8:9]
	v_lshlrev_b64 v[12:13], 11, v[12:13]
	v_lshlrev_b64 v[16:17], 11, v[16:17]
	v_lshlrev_b64 v[20:21], 11, v[20:21]
	v_add_co_u32_e32 v66, vcc, s1, v66
	v_lshl_add_u64 v[0:1], v[88:89], 0, v[0:1]
	v_lshl_add_u64 v[4:5], v[88:89], 0, v[4:5]
	v_lshl_add_u64 v[8:9], v[88:89], 0, v[8:9]
	v_lshl_add_u64 v[12:13], v[88:89], 0, v[12:13]
	v_lshl_add_u64 v[16:17], v[88:89], 0, v[16:17]
	v_lshl_add_u64 v[20:21], v[88:89], 0, v[20:21]
	v_addc_co_u32_e32 v67, vcc, 0, v67, vcc
	global_load_dwordx4 v[0:3], v[0:1], off offset:1024
	v_sub_u32_e32 v113, v87, v94
	global_load_dwordx4 v[4:7], v[4:5], off offset:1024
	v_add_u32_e32 v118, v97, v94
	global_load_dwordx4 v[8:11], v[8:9], off offset:1024
	v_max_i32_e32 v113, v113, v105
	global_load_dwordx4 v[12:15], v[12:13], off offset:1024
	v_min_u32_e32 v118, v118, v106
	global_load_dwordx4 v[16:19], v[16:17], off offset:1024
	v_cmp_ge_i32_e32 vcc, v104, v113
	global_load_dwordx4 v[20:23], v[20:21], off offset:1024
	s_nop 0
	global_load_dwordx4 v[114:117], v[66:67], off
	s_nop 0
	global_load_dwordx4 v[66:69], v[66:67], off offset:1024
	v_cmp_le_i32_e64 s[8:9], v104, v118
	s_and_b64 vcc, vcc, s[8:9]
	s_waitcnt vmcnt(18)
; __device__ __forceinline__ unsigned pk2(float lo, float hi) { const v2f_t f = {lo, hi}; const v2bf_t b = __builtin_convertvector(f, v2bf_t); return __builtin_bit_cast(unsigned, b); }
; __device__ __forceinline__ float bflo(unsigned w) { return __uint_as_float(w << 16); }
; __device__ __forceinline__ float bfhi(unsigned w) { return __uint_as_float(w & 0xffff0000u); }
; __device__ __forceinline__ void mix_resid_rows(const Params& p, int nr, int wg0, int nwg) {
;     ...
;         for (int it = 0; it < 2; ++it) {
;             const int c = it * 512 + lane * 8, gi = c >> 8, hw = 1 << gi;
;             const int lo = max(t - hw, seg0), hi = min(t + hw - 1, seg1);
;             const int kmax = it == 0 ? 4 : 16, tb = t - kmax / 2;
;             float s[8];
; #pragma unroll
;             for (int j = 0; j < 8; ++j) s[j] = 0.f;
; #pragma unroll
;             for (int k = 0; k < kmax; ++k) { const int tt = tb + k; const bool ok = tt >= lo && tt <= hi;
;                 u32x4 uw = it == 0 ? pw0[k & 3] : pw1[k];
;                 if (!ok) uw = (u32x4){0u, 0u, 0u, 0u};
;                 s[0] += bflo(uw.x); s[1] += bfhi(uw.x); s[2] += bflo(uw.y); s[3] += bfhi(uw.y); s[4] += bflo(uw.z); s[5] += bfhi(uw.z); s[6] += bflo(uw.w); s[7] += bfhi(uw.w); }
;             const float inv = 1.f / (float)(hi - lo + 1);
;             const u32x4 ucv = uc[it];
;             u32x4 w; w.x = pk2(s[0] * inv - bflo(ucv.x), s[1] * inv - bfhi(ucv.x)); w.y = pk2(s[2] * inv - bflo(ucv.y), s[3] * inv - bfhi(ucv.y));
;             w.z = pk2(s[4] * inv - bflo(ucv.z), s[5] * inv - bfhi(ucv.z)); w.w = pk2(s[6] * inv - bflo(ucv.w), s[7] * inv - bfhi(ucv.w));
;             *(u32x4*)(mixed + (size_t)r * D + 1024 + c) = w;
	v_cndmask_b32_e32 v121, 0, v71, vcc
	v_cndmask_b32_e32 v71, 0, v70, vcc
	v_sub_u32_e32 v70, v118, v113
	v_add_u32_e32 v70, 1, v70
	v_cndmask_b32_e32 v119, 0, v73, vcc
	v_cndmask_b32_e32 v120, 0, v72, vcc
	v_cmp_gt_u32_e32 vcc, v87, v113
	v_cmp_le_i32_e64 s[8:9], v97, v118
	v_cvt_f32_i32_e32 v70, v70
	s_and_b64 vcc, vcc, s[8:9]
	s_waitcnt vmcnt(17)
	v_cndmask_b32_e32 v122, 0, v77, vcc
	v_cndmask_b32_e32 v123, 0, v76, vcc
	v_cndmask_b32_e32 v75, 0, v75, vcc
	v_cndmask_b32_e32 v73, 0, v74, vcc
	v_cmp_le_u32_e32 vcc, v87, v118
	v_cmp_lt_u32_e64 s[8:9], v87, v118
	s_mov_b32 s1, 0x8800000
	s_waitcnt vmcnt(16)
	v_cndmask_b32_e32 v81, 0, v81, vcc
	v_cndmask_b32_e32 v80, 0, v80, vcc
	v_cndmask_b32_e32 v79, 0, v79, vcc
	v_cndmask_b32_e32 v76, 0, v78, vcc
	v_cmp_ge_u32_e32 vcc, v96, v113
	s_and_b64 vcc, vcc, s[8:9]
	v_div_scale_f32 v72, s[8:9], v70, v70, 1.0
	v_rcp_f32_e32 v74, v72
	s_waitcnt vmcnt(14)
	v_cndmask_b32_e32 v77, 0, v82, vcc
	v_cndmask_b32_e32 v85, 0, v85, vcc
	v_cndmask_b32_e32 v78, 0, v84, vcc
	v_fma_f32 v82, -v72, v74, 1.0
	v_cndmask_b32_e32 v83, 0, v83, vcc
	v_fmac_f32_e32 v74, v82, v74
	v_div_scale_f32 v82, vcc, 1.0, v70, 1.0
	v_mul_f32_e32 v84, v82, v74
	v_fma_f32 v113, -v72, v84, v82
	v_fmac_f32_e32 v84, v113, v74
	v_fma_f32 v72, -v72, v84, v82
	v_div_fmas_f32 v72, v72, v74, v84
	v_div_fixup_f32 v74, v72, v70, 1.0
	v_lshlrev_b32_e32 v70, 16, v71
	v_and_b32_e32 v71, 0xffff0000, v71
	v_pk_add_f32 v[70:71], v[70:71], 0 op_sel_hi:[1,0]
	v_lshlrev_b32_e32 v72, 16, v73
	v_and_b32_e32 v73, 0xffff0000, v73
	v_pk_add_f32 v[70:71], v[70:71], v[72:73]
	v_lshlrev_b32_e32 v72, 16, v76
	v_and_b32_e32 v73, 0xffff0000, v76
	v_pk_add_f32 v[70:71], v[70:71], v[72:73]
	v_lshlrev_b32_e32 v72, 16, v77
	v_and_b32_e32 v73, 0xffff0000, v77
	v_pk_add_f32 v[70:71], v[70:71], v[72:73]
	v_lshlrev_b32_e32 v76, 16, v75
	v_and_b32_e32 v77, 0xffff0000, v75
	v_add_u32_e32 v86, s88, v86
	v_lshl_add_u64 v[92:93], v[92:93], 0, s[12:13]
	s_waitcnt vmcnt(1)
	v_lshlrev_b32_e32 v72, 16, v114
	v_and_b32_e32 v73, 0xffff0000, v114
	v_pk_fma_f32 v[70:71], v[74:75], v[70:71], v[72:73] op_sel_hi:[0,1,1] neg_lo:[0,0,1] neg_hi:[0,0,1]
	v_lshlrev_b32_e32 v72, 16, v121
	v_and_b32_e32 v73, 0xffff0000, v121
	v_pk_add_f32 v[72:73], v[72:73], 0 op_sel_hi:[1,0]
	v_cvt_pk_bf16_f32 v70, v70, v71
	v_pk_add_f32 v[72:73], v[72:73], v[76:77]
	v_lshlrev_b32_e32 v76, 16, v79
	v_and_b32_e32 v77, 0xffff0000, v79
	v_pk_add_f32 v[72:73], v[72:73], v[76:77]
	v_lshlrev_b32_e32 v76, 16, v83
	v_and_b32_e32 v77, 0xffff0000, v83
	v_pk_add_f32 v[72:73], v[72:73], v[76:77]
	v_lshlrev_b32_e32 v76, 16, v115
	v_and_b32_e32 v77, 0xffff0000, v115
	v_pk_fma_f32 v[72:73], v[74:75], v[72:73], v[76:77] op_sel_hi:[0,1,1] neg_lo:[0,0,1] neg_hi:[0,0,1]
	v_cvt_pk_bf16_f32 v71, v72, v73
	v_lshlrev_b32_e32 v72, 16, v120
	v_and_b32_e32 v73, 0xffff0000, v120
	v_pk_add_f32 v[72:73], v[72:73], 0 op_sel_hi:[1,0]
	v_lshlrev_b32_e32 v76, 16, v123
	v_and_b32_e32 v77, 0xffff0000, v123
	v_pk_add_f32 v[72:73], v[72:73], v[76:77]
	v_lshlrev_b32_e32 v76, 16, v80
	v_and_b32_e32 v77, 0xffff0000, v80
	v_pk_add_f32 v[72:73], v[72:73], v[76:77]
	v_lshlrev_b32_e32 v76, 16, v78
	v_and_b32_e32 v77, 0xffff0000, v78
	v_pk_add_f32 v[72:73], v[72:73], v[76:77]
	v_lshlrev_b32_e32 v76, 16, v116
	v_and_b32_e32 v77, 0xffff0000, v116
	v_pk_fma_f32 v[72:73], v[74:75], v[72:73], v[76:77] op_sel_hi:[0,1,1] neg_lo:[0,0,1] neg_hi:[0,0,1]
	v_lshlrev_b32_e32 v76, 16, v119
	v_and_b32_e32 v77, 0xffff0000, v119
	v_pk_add_f32 v[76:77], v[76:77], 0 op_sel_hi:[1,0]
	v_lshlrev_b32_e32 v78, 16, v122
	v_and_b32_e32 v79, 0xffff0000, v122
	v_pk_add_f32 v[76:77], v[76:77], v[78:79]
	v_lshlrev_b32_e32 v78, 16, v81
	v_and_b32_e32 v79, 0xffff0000, v81
	v_pk_add_f32 v[76:77], v[76:77], v[78:79]
	v_lshlrev_b32_e32 v78, 16, v85
	v_and_b32_e32 v79, 0xffff0000, v85
	v_pk_add_f32 v[76:77], v[76:77], v[78:79]
	v_lshlrev_b32_e32 v78, 16, v117
	v_and_b32_e32 v79, 0xffff0000, v117
	v_pk_fma_f32 v[74:75], v[74:75], v[76:77], v[78:79] op_sel_hi:[0,1,1] neg_lo:[0,0,1] neg_hi:[0,0,1]
	v_cvt_pk_bf16_f32 v72, v72, v73
	v_cvt_pk_bf16_f32 v73, v74, v75
	v_lshl_add_u64 v[74:75], v[90:91], 0, v[64:65]
	v_add_co_u32_e32 v74, vcc, s1, v74
	s_movk_i32 s1, 0x3fff
	s_nop 0
	v_addc_co_u32_e32 v75, vcc, 0, v75, vcc
	global_store_dwordx4 v[74:75], v[70:73], off offset:2048
	v_lshl_add_u64 v[90:91], v[90:91], 0, s[90:91]
	s_nop 0
	v_sub_u32_e32 v70, v87, v95
	v_add_u32_e32 v71, v97, v95
	v_max_i32_e32 v70, v70, v105
	v_min_u32_e32 v71, v71, v106
	v_cmp_ge_i32_e32 vcc, v107, v70
	v_cmp_le_i32_e64 s[8:9], v107, v71
	s_and_b64 vcc, vcc, s[8:9]
	v_cndmask_b32_e32 v72, 0, v43, vcc
	v_cndmask_b32_e32 v42, 0, v42, vcc
	v_cndmask_b32_e32 v41, 0, v41, vcc
	v_cndmask_b32_e32 v40, 0, v40, vcc
	v_cmp_ge_i32_e32 vcc, v108, v70
	v_cmp_le_i32_e64 s[8:9], v108, v71
	s_and_b64 vcc, vcc, s[8:9]
	v_cndmask_b32_e32 v47, 0, v47, vcc
	v_cndmask_b32_e32 v43, 0, v46, vcc
	v_cndmask_b32_e32 v45, 0, v45, vcc
	v_cndmask_b32_e32 v44, 0, v44, vcc
	v_cmp_ge_i32_e32 vcc, v109, v70
	v_cmp_le_i32_e64 s[8:9], v109, v71
	s_and_b64 vcc, vcc, s[8:9]
	v_cndmask_b32_e32 v46, 0, v51, vcc
	v_cndmask_b32_e32 v50, 0, v50, vcc
	v_cndmask_b32_e32 v49, 0, v49, vcc
	v_cndmask_b32_e32 v48, 0, v48, vcc
	v_cmp_ge_i32_e32 vcc, v110, v70
	v_cmp_le_i32_e64 s[8:9], v110, v71
	s_and_b64 vcc, vcc, s[8:9]
	v_cndmask_b32_e32 v51, 0, v55, vcc
	v_cndmask_b32_e32 v54, 0, v54, vcc
	v_cndmask_b32_e32 v53, 0, v53, vcc
	v_cndmask_b32_e32 v52, 0, v52, vcc
	v_cmp_ge_i32_e32 vcc, v111, v70
	v_cmp_le_i32_e64 s[8:9], v111, v71
	s_and_b64 vcc, vcc, s[8:9]
	v_cndmask_b32_e32 v55, 0, v59, vcc
	v_cndmask_b32_e32 v58, 0, v58, vcc
	v_cndmask_b32_e32 v57, 0, v57, vcc
; __device__ __forceinline__ unsigned pk2(float lo, float hi) { const v2f_t f = {lo, hi}; const v2bf_t b = __builtin_convertvector(f, v2bf_t); return __builtin_bit_cast(unsigned, b); }
; __device__ __forceinline__ float bflo(unsigned w) { return __uint_as_float(w << 16); }
; __device__ __forceinline__ float bfhi(unsigned w) { return __uint_as_float(w & 0xffff0000u); }
; __device__ __forceinline__ void mix_resid_rows(const Params& p, int nr, int wg0, int nwg) {
;     ...
;         for (int it = 0; it < 2; ++it) {
;             const int c = it * 512 + lane * 8, gi = c >> 8, hw = 1 << gi;
;             const int lo = max(t - hw, seg0), hi = min(t + hw - 1, seg1);
;             const int kmax = it == 0 ? 4 : 16, tb = t - kmax / 2;
;             float s[8];
; #pragma unroll
;             for (int j = 0; j < 8; ++j) s[j] = 0.f;
; #pragma unroll
;             for (int k = 0; k < kmax; ++k) { const int tt = tb + k; const bool ok = tt >= lo && tt <= hi;
;                 u32x4 uw = it == 0 ? pw0[k & 3] : pw1[k];
;                 if (!ok) uw = (u32x4){0u, 0u, 0u, 0u};
;                 s[0] += bflo(uw.x); s[1] += bfhi(uw.x); s[2] += bflo(uw.y); s[3] += bfhi(uw.y); s[4] += bflo(uw.z); s[5] += bfhi(uw.z); s[6] += bflo(uw.w); s[7] += bfhi(uw.w); }
;             const float inv = 1.f / (float)(hi - lo + 1);
;             const u32x4 ucv = uc[it];
;             u32x4 w; w.x = pk2(s[0] * inv - bflo(ucv.x), s[1] * inv - bfhi(ucv.x)); w.y = pk2(s[2] * inv - bflo(ucv.y), s[3] * inv - bfhi(ucv.y));
;             w.z = pk2(s[4] * inv - bflo(ucv.z), s[5] * inv - bfhi(ucv.z)); w.w = pk2(s[6] * inv - bflo(ucv.w), s[7] * inv - bfhi(ucv.w));
;             *(u32x4*)(mixed + (size_t)r * D + 1024 + c) = w;
	v_cndmask_b32_e32 v56, 0, v56, vcc
	v_cmp_ge_i32_e32 vcc, v112, v70
	v_cmp_le_i32_e64 s[8:9], v112, v71
	s_and_b64 vcc, vcc, s[8:9]
	v_cndmask_b32_e32 v59, 0, v63, vcc
	v_cndmask_b32_e32 v62, 0, v62, vcc
	v_cndmask_b32_e32 v61, 0, v61, vcc
	v_cndmask_b32_e32 v60, 0, v60, vcc
	v_cmp_ge_i32_e32 vcc, v104, v70
	v_cmp_le_i32_e64 s[8:9], v104, v71
	s_and_b64 vcc, vcc, s[8:9]
	v_cndmask_b32_e32 v76, 0, v37, vcc
	v_cndmask_b32_e32 v77, 0, v36, vcc
	v_lshlrev_b32_e32 v36, 16, v40
	v_and_b32_e32 v37, 0xffff0000, v40
	v_cndmask_b32_e32 v63, 0, v39, vcc
	v_cndmask_b32_e32 v73, 0, v38, vcc
	v_pk_add_f32 v[36:37], v[36:37], 0 op_sel_hi:[1,0]
	v_lshlrev_b32_e32 v38, 16, v44
	v_and_b32_e32 v39, 0xffff0000, v44
	v_pk_add_f32 v[36:37], v[36:37], v[38:39]
	v_lshlrev_b32_e32 v38, 16, v48
	v_and_b32_e32 v39, 0xffff0000, v48
	v_pk_add_f32 v[36:37], v[36:37], v[38:39]
	v_lshlrev_b32_e32 v38, 16, v52
	v_and_b32_e32 v39, 0xffff0000, v52
	v_pk_add_f32 v[36:37], v[36:37], v[38:39]
	v_lshlrev_b32_e32 v38, 16, v56
	v_and_b32_e32 v39, 0xffff0000, v56
	v_pk_add_f32 v[36:37], v[36:37], v[38:39]
	v_lshlrev_b32_e32 v38, 16, v60
	v_and_b32_e32 v39, 0xffff0000, v60
	v_pk_add_f32 v[36:37], v[36:37], v[38:39]
	v_lshlrev_b32_e32 v38, 16, v77
	v_and_b32_e32 v39, 0xffff0000, v77
	v_pk_add_f32 v[36:37], v[36:37], v[38:39]
	v_lshlrev_b32_e32 v38, 16, v41
	v_and_b32_e32 v39, 0xffff0000, v41
	v_pk_add_f32 v[38:39], v[38:39], 0 op_sel_hi:[1,0]
	v_lshlrev_b32_e32 v40, 16, v45
	v_and_b32_e32 v41, 0xffff0000, v45
	v_pk_add_f32 v[38:39], v[38:39], v[40:41]
	v_lshlrev_b32_e32 v40, 16, v49
	v_and_b32_e32 v41, 0xffff0000, v49
	v_pk_add_f32 v[38:39], v[38:39], v[40:41]
	v_lshlrev_b32_e32 v40, 16, v53
	v_and_b32_e32 v41, 0xffff0000, v53
	v_pk_add_f32 v[38:39], v[38:39], v[40:41]
	v_lshlrev_b32_e32 v40, 16, v57
	v_and_b32_e32 v41, 0xffff0000, v57
	v_pk_add_f32 v[38:39], v[38:39], v[40:41]
	v_lshlrev_b32_e32 v40, 16, v61
	v_and_b32_e32 v41, 0xffff0000, v61
	v_pk_add_f32 v[38:39], v[38:39], v[40:41]
	v_lshlrev_b32_e32 v40, 16, v76
	v_and_b32_e32 v41, 0xffff0000, v76
	v_pk_add_f32 v[38:39], v[38:39], v[40:41]
	v_lshlrev_b32_e32 v40, 16, v42
	v_and_b32_e32 v41, 0xffff0000, v42
	v_pk_add_f32 v[40:41], v[40:41], 0 op_sel_hi:[1,0]
	v_lshlrev_b32_e32 v42, 16, v43
	v_and_b32_e32 v43, 0xffff0000, v43
	v_pk_add_f32 v[40:41], v[40:41], v[42:43]
	v_lshlrev_b32_e32 v42, 16, v50
	v_and_b32_e32 v43, 0xffff0000, v50
	v_pk_add_f32 v[40:41], v[40:41], v[42:43]
	v_lshlrev_b32_e32 v42, 16, v54
	v_and_b32_e32 v43, 0xffff0000, v54
	v_pk_add_f32 v[40:41], v[40:41], v[42:43]
	v_lshlrev_b32_e32 v42, 16, v58
	v_and_b32_e32 v43, 0xffff0000, v58
	v_pk_add_f32 v[40:41], v[40:41], v[42:43]
	v_lshlrev_b32_e32 v42, 16, v62
	v_and_b32_e32 v43, 0xffff0000, v62
	v_pk_add_f32 v[40:41], v[40:41], v[42:43]
	v_lshlrev_b32_e32 v42, 16, v73
	v_and_b32_e32 v43, 0xffff0000, v73
	v_pk_add_f32 v[40:41], v[40:41], v[42:43]
	v_lshlrev_b32_e32 v42, 16, v72
	v_and_b32_e32 v43, 0xffff0000, v72
	v_pk_add_f32 v[42:43], v[42:43], 0 op_sel_hi:[1,0]
	v_lshlrev_b32_e32 v44, 16, v47
	v_and_b32_e32 v45, 0xffff0000, v47
	v_pk_add_f32 v[42:43], v[42:43], v[44:45]
	v_lshlrev_b32_e32 v44, 16, v46
	v_and_b32_e32 v45, 0xffff0000, v46
	v_pk_add_f32 v[42:43], v[42:43], v[44:45]
	v_lshlrev_b32_e32 v44, 16, v51
	v_and_b32_e32 v45, 0xffff0000, v51
	v_pk_add_f32 v[42:43], v[42:43], v[44:45]
	v_lshlrev_b32_e32 v44, 16, v55
	v_and_b32_e32 v45, 0xffff0000, v55
	v_pk_add_f32 v[42:43], v[42:43], v[44:45]
	v_lshlrev_b32_e32 v44, 16, v59
	v_and_b32_e32 v45, 0xffff0000, v59
	v_cmp_gt_u32_e32 vcc, v87, v70
	v_cmp_le_i32_e64 s[8:9], v97, v71
	v_pk_add_f32 v[42:43], v[42:43], v[44:45]
	v_lshlrev_b32_e32 v44, 16, v63
	v_and_b32_e32 v45, 0xffff0000, v63
	s_and_b64 vcc, vcc, s[8:9]
	v_pk_add_f32 v[42:43], v[42:43], v[44:45]
	v_cndmask_b32_e32 v47, 0, v35, vcc
	v_cndmask_b32_e32 v45, 0, v34, vcc
	v_cndmask_b32_e32 v35, 0, v33, vcc
	v_cndmask_b32_e32 v33, 0, v32, vcc
	v_cmp_le_u32_e32 vcc, v87, v71
	v_cmp_lt_u32_e64 s[8:9], v87, v71
	v_lshlrev_b32_e32 v32, 16, v33
	v_cndmask_b32_e32 v51, 0, v31, vcc
	v_cndmask_b32_e32 v49, 0, v30, vcc
	v_cndmask_b32_e32 v31, 0, v29, vcc
	v_cndmask_b32_e32 v29, 0, v28, vcc
	v_cmp_ge_u32_e32 vcc, v96, v70
	s_and_b64 vcc, vcc, s[8:9]
	v_cmp_le_u32_e64 s[8:9], v98, v71
	v_cndmask_b32_e32 v55, 0, v27, vcc
	v_cndmask_b32_e32 v53, 0, v26, vcc
	v_cndmask_b32_e32 v27, 0, v25, vcc
	v_cndmask_b32_e32 v25, 0, v24, vcc
	v_cmp_ge_u32_e32 vcc, v98, v70
	s_and_b64 vcc, vcc, s[8:9]
	v_cmp_le_u32_e64 s[8:9], v99, v71
	v_cndmask_b32_e32 v56, 0, v3, vcc
	v_cndmask_b32_e32 v57, 0, v2, vcc
	v_cndmask_b32_e32 v58, 0, v1, vcc
	v_cndmask_b32_e32 v3, 0, v0, vcc
	v_cmp_ge_u32_e32 vcc, v99, v70
	s_and_b64 vcc, vcc, s[8:9]
	v_cmp_le_u32_e64 s[8:9], v100, v71
	v_cndmask_b32_e32 v59, 0, v7, vcc
	v_cndmask_b32_e32 v60, 0, v6, vcc
	v_cndmask_b32_e32 v5, 0, v5, vcc
	v_cndmask_b32_e32 v6, 0, v4, vcc
	v_cmp_ge_u32_e32 vcc, v100, v70
	s_and_b64 vcc, vcc, s[8:9]
	v_sub_u32_e32 v0, v71, v70
	v_cndmask_b32_e32 v11, 0, v11, vcc
	v_cndmask_b32_e32 v10, 0, v10, vcc
	v_cndmask_b32_e32 v9, 0, v9, vcc
	v_cndmask_b32_e32 v7, 0, v8, vcc
	v_cmp_ge_u32_e32 vcc, v101, v70
	v_cmp_le_u32_e64 s[8:9], v101, v71
	v_add_u32_e32 v0, 1, v0
	s_and_b64 vcc, vcc, s[8:9]
	v_cvt_f32_i32_e32 v0, v0
	v_cndmask_b32_e32 v15, 0, v15, vcc
	v_cndmask_b32_e32 v8, 0, v14, vcc
	v_cndmask_b32_e32 v13, 0, v13, vcc
	v_cndmask_b32_e32 v12, 0, v12, vcc
	v_cmp_ge_u32_e32 vcc, v102, v70
	v_cmp_le_u32_e64 s[8:9], v102, v71
; __device__ __forceinline__ unsigned pk2(float lo, float hi) { const v2f_t f = {lo, hi}; const v2bf_t b = __builtin_convertvector(f, v2bf_t); return __builtin_bit_cast(unsigned, b); }
; __device__ __forceinline__ float bflo(unsigned w) { return __uint_as_float(w << 16); }
; __device__ __forceinline__ float bfhi(unsigned w) { return __uint_as_float(w & 0xffff0000u); }
; __device__ __forceinline__ void mix_resid_rows(const Params& p, int nr, int wg0, int nwg) {
;     ...
;             for (int k = 0; k < kmax; ++k) { const int tt = tb + k; const bool ok = tt >= lo && tt <= hi;
;                 u32x4 uw = it == 0 ? pw0[k & 3] : pw1[k];
;                 if (!ok) uw = (u32x4){0u, 0u, 0u, 0u};
;                 s[0] += bflo(uw.x); s[1] += bfhi(uw.x); s[2] += bflo(uw.y); s[3] += bfhi(uw.y); s[4] += bflo(uw.z); s[5] += bfhi(uw.z); s[6] += bflo(uw.w); s[7] += bfhi(uw.w); }
;             const float inv = 1.f / (float)(hi - lo + 1);
;             const u32x4 ucv = uc[it];
;             u32x4 w; w.x = pk2(s[0] * inv - bflo(ucv.x), s[1] * inv - bfhi(ucv.x)); w.y = pk2(s[2] * inv - bflo(ucv.y), s[3] * inv - bfhi(ucv.y));
;             w.z = pk2(s[4] * inv - bflo(ucv.z), s[5] * inv - bfhi(ucv.z)); w.w = pk2(s[6] * inv - bflo(ucv.w), s[7] * inv - bfhi(ucv.w));
;             *(u32x4*)(mixed + (size_t)r * D + 1024 + c) = w;
	s_and_b64 vcc, vcc, s[8:9]
	v_cndmask_b32_e32 v14, 0, v19, vcc
	v_cndmask_b32_e32 v18, 0, v18, vcc
	v_cndmask_b32_e32 v17, 0, v17, vcc
	v_cndmask_b32_e32 v16, 0, v16, vcc
	v_cmp_ge_u32_e32 vcc, v103, v70
	v_cmp_le_u32_e64 s[8:9], v103, v71
	s_and_b64 vcc, vcc, s[8:9]
	v_div_scale_f32 v1, s[8:9], v0, v0, 1.0
	v_rcp_f32_e32 v2, v1
	v_cndmask_b32_e32 v19, 0, v23, vcc
	v_cndmask_b32_e32 v22, 0, v22, vcc
	v_cndmask_b32_e32 v21, 0, v21, vcc
	v_fma_f32 v4, -v1, v2, 1.0
	v_cndmask_b32_e32 v20, 0, v20, vcc
	v_fmac_f32_e32 v2, v4, v2
	v_div_scale_f32 v4, vcc, 1.0, v0, 1.0
	v_mul_f32_e32 v23, v4, v2
	v_fma_f32 v61, -v1, v23, v4
	v_fmac_f32_e32 v23, v61, v2
	v_fma_f32 v1, -v1, v23, v4
	v_and_b32_e32 v33, 0xffff0000, v33
	v_div_fmas_f32 v1, v1, v2, v23
	v_lshlrev_b32_e32 v28, 16, v29
	v_and_b32_e32 v29, 0xffff0000, v29
	v_div_fixup_f32 v4, v1, v0, 1.0
	v_pk_add_f32 v[0:1], v[36:37], v[32:33]
	v_lshlrev_b32_e32 v24, 16, v25
	v_and_b32_e32 v25, 0xffff0000, v25
	v_pk_add_f32 v[0:1], v[0:1], v[28:29]
	v_lshlrev_b32_e32 v2, 16, v3
	v_pk_add_f32 v[0:1], v[0:1], v[24:25]
	v_and_b32_e32 v3, 0xffff0000, v3
	v_pk_add_f32 v[0:1], v[0:1], v[2:3]
	v_lshlrev_b32_e32 v2, 16, v6
	v_and_b32_e32 v3, 0xffff0000, v6
	v_pk_add_f32 v[0:1], v[0:1], v[2:3]
	v_lshlrev_b32_e32 v2, 16, v7
	v_and_b32_e32 v3, 0xffff0000, v7
	v_pk_add_f32 v[0:1], v[0:1], v[2:3]
	v_lshlrev_b32_e32 v2, 16, v12
	v_and_b32_e32 v3, 0xffff0000, v12
	v_pk_add_f32 v[0:1], v[0:1], v[2:3]
	v_lshlrev_b32_e32 v2, 16, v16
	v_and_b32_e32 v3, 0xffff0000, v16
	v_pk_add_f32 v[0:1], v[0:1], v[2:3]
	v_lshlrev_b32_e32 v2, 16, v20
	v_and_b32_e32 v3, 0xffff0000, v20
	v_lshlrev_b32_e32 v34, 16, v35
	v_and_b32_e32 v35, 0xffff0000, v35
	v_pk_add_f32 v[0:1], v[0:1], v[2:3]
	s_waitcnt vmcnt(1)
	v_lshlrev_b32_e32 v2, 16, v66
	v_and_b32_e32 v3, 0xffff0000, v66
	v_lshlrev_b32_e32 v30, 16, v31
	v_and_b32_e32 v31, 0xffff0000, v31
	v_pk_fma_f32 v[0:1], v[4:5], v[0:1], v[2:3] op_sel_hi:[0,1,1] neg_lo:[0,0,1] neg_hi:[0,0,1]
	v_pk_add_f32 v[2:3], v[38:39], v[34:35]
	v_lshlrev_b32_e32 v26, 16, v27
	v_and_b32_e32 v27, 0xffff0000, v27
	v_pk_add_f32 v[2:3], v[2:3], v[30:31]
	v_lshlrev_b32_e32 v6, 16, v58
	v_pk_add_f32 v[2:3], v[2:3], v[26:27]
	v_and_b32_e32 v7, 0xffff0000, v58
	v_pk_add_f32 v[2:3], v[2:3], v[6:7]
	v_lshlrev_b32_e32 v6, 16, v5
	v_and_b32_e32 v7, 0xffff0000, v5
	v_pk_add_f32 v[2:3], v[2:3], v[6:7]
	v_lshlrev_b32_e32 v6, 16, v9
	v_and_b32_e32 v7, 0xffff0000, v9
	v_pk_add_f32 v[2:3], v[2:3], v[6:7]
	v_lshlrev_b32_e32 v6, 16, v13
	v_and_b32_e32 v7, 0xffff0000, v13
	v_pk_add_f32 v[2:3], v[2:3], v[6:7]
	v_lshlrev_b32_e32 v6, 16, v17
	v_and_b32_e32 v7, 0xffff0000, v17
	v_pk_add_f32 v[2:3], v[2:3], v[6:7]
	v_lshlrev_b32_e32 v6, 16, v21
	v_and_b32_e32 v7, 0xffff0000, v21
	v_pk_add_f32 v[2:3], v[2:3], v[6:7]
	v_lshlrev_b32_e32 v6, 16, v67
	v_and_b32_e32 v7, 0xffff0000, v67
	v_lshlrev_b32_e32 v44, 16, v45
	v_and_b32_e32 v45, 0xffff0000, v45
	v_pk_fma_f32 v[2:3], v[4:5], v[2:3], v[6:7] op_sel_hi:[0,1,1] neg_lo:[0,0,1] neg_hi:[0,0,1]
	v_lshlrev_b32_e32 v48, 16, v49
	v_and_b32_e32 v49, 0xffff0000, v49
	v_cvt_pk_bf16_f32 v0, v0, v1
	v_cvt_pk_bf16_f32 v1, v2, v3
	v_pk_add_f32 v[2:3], v[40:41], v[44:45]
	v_lshlrev_b32_e32 v52, 16, v53
	v_and_b32_e32 v53, 0xffff0000, v53
	v_pk_add_f32 v[2:3], v[2:3], v[48:49]
	v_lshlrev_b32_e32 v6, 16, v57
	v_pk_add_f32 v[2:3], v[2:3], v[52:53]
	v_and_b32_e32 v7, 0xffff0000, v57
	v_pk_add_f32 v[2:3], v[2:3], v[6:7]
	v_lshlrev_b32_e32 v6, 16, v60
	v_and_b32_e32 v7, 0xffff0000, v60
	v_pk_add_f32 v[2:3], v[2:3], v[6:7]
	v_lshlrev_b32_e32 v6, 16, v10
	v_and_b32_e32 v7, 0xffff0000, v10
	v_pk_add_f32 v[2:3], v[2:3], v[6:7]
	v_lshlrev_b32_e32 v6, 16, v8
	v_and_b32_e32 v7, 0xffff0000, v8
	v_pk_add_f32 v[2:3], v[2:3], v[6:7]
	v_lshlrev_b32_e32 v6, 16, v18
	v_and_b32_e32 v7, 0xffff0000, v18
	v_pk_add_f32 v[2:3], v[2:3], v[6:7]
	v_lshlrev_b32_e32 v6, 16, v22
	v_and_b32_e32 v7, 0xffff0000, v22
	v_lshlrev_b32_e32 v46, 16, v47
	v_and_b32_e32 v47, 0xffff0000, v47
	v_pk_add_f32 v[2:3], v[2:3], v[6:7]
	v_lshlrev_b32_e32 v6, 16, v68
	v_and_b32_e32 v7, 0xffff0000, v68
	v_lshlrev_b32_e32 v50, 16, v51
	v_and_b32_e32 v51, 0xffff0000, v51
	v_pk_fma_f32 v[2:3], v[4:5], v[2:3], v[6:7] op_sel_hi:[0,1,1] neg_lo:[0,0,1] neg_hi:[0,0,1]
	v_pk_add_f32 v[6:7], v[42:43], v[46:47]
	v_lshlrev_b32_e32 v54, 16, v55
	v_and_b32_e32 v55, 0xffff0000, v55
	v_pk_add_f32 v[6:7], v[6:7], v[50:51]
	v_lshlrev_b32_e32 v8, 16, v56
	v_pk_add_f32 v[6:7], v[6:7], v[54:55]
	v_and_b32_e32 v9, 0xffff0000, v56
	v_pk_add_f32 v[6:7], v[6:7], v[8:9]
	v_lshlrev_b32_e32 v8, 16, v59
	v_and_b32_e32 v9, 0xffff0000, v59
	v_pk_add_f32 v[6:7], v[6:7], v[8:9]
	v_lshlrev_b32_e32 v8, 16, v11
	v_and_b32_e32 v9, 0xffff0000, v11
	v_pk_add_f32 v[6:7], v[6:7], v[8:9]
	v_lshlrev_b32_e32 v8, 16, v15
	v_and_b32_e32 v9, 0xffff0000, v15
	v_pk_add_f32 v[6:7], v[6:7], v[8:9]
	v_lshlrev_b32_e32 v8, 16, v14
	v_and_b32_e32 v9, 0xffff0000, v14
	v_pk_add_f32 v[6:7], v[6:7], v[8:9]
	v_lshlrev_b32_e32 v8, 16, v19
	v_and_b32_e32 v9, 0xffff0000, v19
	v_pk_add_f32 v[6:7], v[6:7], v[8:9]
	v_lshlrev_b32_e32 v8, 16, v69
	v_and_b32_e32 v9, 0xffff0000, v69
	v_pk_fma_f32 v[4:5], v[4:5], v[6:7], v[8:9] op_sel_hi:[0,1,1] neg_lo:[0,0,1] neg_hi:[0,0,1]
	v_cmp_lt_i32_e32 vcc, s1, v86
	v_cvt_pk_bf16_f32 v2, v2, v3
	v_cvt_pk_bf16_f32 v3, v4, v5
	s_or_b64 s[10:11], vcc, s[10:11]
	global_store_dwordx4 v[74:75], v[0:3], off offset:3072
	s_andn2_b64 exec, exec, s[10:11]
	s_cbranch_execnz .LBB0_539

; __device__ __forceinline__ int opaque_tid() { int t = threadIdx.x; asm volatile("" : "+v"(t)); return t; }
; #define MIX_LOAD(rr) do { _Pragma("unroll") for (int h = 0; h < 4; ++h) { const size_t o4_ = (size_t)(rr) * 1024 + h * 256 + lane * 4; nof[h] = *(const u32x2*)(of + o4_); nob[h] = *(const u32x2*)(ob + o4_); ngw[h] = *(const u32x2*)(pg + o4_); } } while (0)
; __device__ __forceinline__ Params load_params() { KParams* kp = (KParams*)__builtin_amdgcn_kernarg_segment_ptr(); asm volatile("" : "+s"(kp)); return *kp; }
; #define PH(i) if (PHASE_MASK & (1 << (i))) for (int dup_ = 0; dup_ <= ((DUP_MASK >> (i)) & 1); ++dup_)
; __device__ __forceinline__ void mix_phase(const Params& p, int l, int nrows, int rs_lo  ) {
;     const int tid_ = opaque_tid(), lane = tid_ & 63, wave = tid_ >> 6;
;     unsigned char* C = p.ws + OFF_C;
;     const bf16_t* of = (const bf16_t*)(C + C_OF); const bf16_t* ob = (const bf16_t*)(C + C_OB);
;     const bf16_t* pg = (const bf16_t*)(C + C_PG); const bf16_t* pu = (const bf16_t*)(C + C_PU);
;     bf16_t* mixed = (bf16_t*)(p.ws + OFF_H);
;     const f32x4 ng = *(const f32x4*)(p.gla_norm_g + l * 256 + lane * 4);
;     const int stride = gridDim.x * 8;
;     int r = blockIdx.x * 8 + wave;
;     u32x2 nof[4], nob[4]; u32x2 ngw[4];
;     ...
;     if (r < nrows) MIX_LOAD(r);
; __global__ void __launch_bounds__(512, 2) mega(Params p_unused) {
;     ...
;         PH(5) { const Params p = load_params(); mix_phase(p, l, nrows, l == 1 ? 8192 : 0);
.LBB0_594:
	s_or_b64 exec, exec, s[2:3]
	v_readlane_b32 s8, v239, 2
	v_readlane_b32 s9, v239, 3
	s_and_b64 s[2:3], s[56:57], exec
	s_waitcnt lgkmcnt(0)
	s_barrier
	s_load_dwordx2 s[2:3], s[8:9], 0x28
	s_load_dwordx2 s[12:13], s[8:9], 0xb0
	s_movk_i32 s1, 0x4400
	s_waitcnt vmcnt(5)
	v_mov_b32_e32 v4, v194
	s_cselect_b32 s58, s1, 0x4000
	v_readlane_b32 s1, v239, 6
	v_ashrrev_i32_e32 v0, 6, v4
	s_nop 0
	v_add_u32_e32 v64, s1, v0
	v_cmp_gt_i32_e32 vcc, s58, v64
	s_and_saveexec_b64 s[14:15], vcc
	s_cbranch_execz .LBB0_605
	v_readlane_b32 s10, v238, 4
	v_readlane_b32 s11, v238, 5
	s_and_b64 s[10:11], s[10:11], exec
	s_movk_i32 s1, 0x4000
	s_lshl_b32 s72, s81, 8
	s_add_i32 s24, s58, -1
	s_waitcnt lgkmcnt(0)
	s_add_u32 s16, s12, 0x134fc000
	s_addc_u32 s17, s13, 0
	s_add_u32 s18, s12, 0x2372c000
	s_load_dwordx2 s[10:11], s[8:9], 0x48
	s_addc_u32 s19, s13, 0
	s_add_u32 s20, s12, 0x178fc000
	s_addc_u32 s21, s13, 0
	v_and_b32_e32 v5, 63, v4
	s_add_u32 s8, s12, 0x8800000
	s_waitcnt vmcnt(4)
	v_ashrrev_i32_e32 v9, 31, v64
	v_mov_b32_e32 v8, v64
	s_addc_u32 s9, s13, 0
	s_lshl_b64 s[22:23], s[72:73], 2
	v_lshlrev_b64 v[10:11], 11, v[8:9]
	s_waitcnt vmcnt(0)
	v_lshlrev_b32_e32 v22, 3, v5
	s_waitcnt lgkmcnt(0)
	s_add_u32 s10, s10, s22
	v_or_b32_e32 v10, v10, v22
	s_addc_u32 s11, s11, s23
	v_lshlrev_b32_e32 v6, 4, v5
	v_lshl_add_u64 v[12:13], s[16:17], 0, v[10:11]
	v_lshl_add_u64 v[16:17], s[20:21], 0, v[10:11]
	v_or_b32_e32 v18, 0x200, v10
	v_mov_b32_e32 v19, v11
	global_load_dwordx4 v[0:3], v6, s[10:11]
	v_lshl_add_u64 v[14:15], s[18:19], 0, v[10:11]
	v_lshl_add_u64 v[20:21], s[16:17], 0, v[18:19]
	global_load_dwordx2 v[148:149], v[12:13], off
	global_load_dwordx2 v[146:147], v[14:15], off
	global_load_dwordx2 v[144:145], v[16:17], off
	global_load_dwordx2 v[142:143], v[20:21], off
	v_lshl_add_u64 v[12:13], s[18:19], 0, v[18:19]
	v_or_b32_e32 v16, 0x400, v10
	v_mov_b32_e32 v17, v11
	v_lshl_add_u64 v[14:15], s[20:21], 0, v[18:19]
	v_lshl_add_u64 v[18:19], s[16:17], 0, v[16:17]
	v_lshl_add_u64 v[20:21], s[18:19], 0, v[16:17]
	global_load_dwordx2 v[140:141], v[12:13], off
	global_load_dwordx2 v[138:139], v[14:15], off
	global_load_dwordx2 v[136:137], v[18:19], off
	global_load_dwordx2 v[134:135], v[20:21], off
	v_lshl_add_u64 v[12:13], s[20:21], 0, v[16:17]
	v_or_b32_e32 v10, 0x600, v10
	v_lshl_add_u64 v[14:15], s[16:17], 0, v[10:11]
	v_lshl_add_u64 v[16:17], s[18:19], 0, v[10:11]
	v_lshl_add_u64 v[10:11], s[20:21], 0, v[10:11]
	global_load_dwordx2 v[132:133], v[12:13], off
	global_load_dwordx2 v[130:131], v[14:15], off
	global_load_dwordx2 v[128:129], v[16:17], off
	global_load_dwordx2 v[126:127], v[10:11], off
	v_mov_b32_e32 v7, v65
	v_lshl_add_u64 v[10:11], s[12:13], 0, v[6:7]
	s_mov_b64 s[10:11], 0x19afc000
	v_lshl_add_u64 v[96:97], v[10:11], 0, s[10:11]
	v_and_b32_e32 v10, 64, v202
	v_add_u32_e32 v10, 64, v10
	v_xor_b32_e32 v11, 1, v202
	v_cmp_lt_i32_e32 vcc, v11, v10
	v_bfe_u32 v4, v4, 5, 1
	v_lshlrev_b32_e64 v155, v4, 1
	v_cndmask_b32_e32 v11, v202, v11, vcc
	v_lshlrev_b32_e32 v95, 2, v11
	v_xor_b32_e32 v11, 2, v202
	v_cmp_lt_i32_e32 vcc, v11, v10
	v_bfe_u32 v4, v5, 5, 24
	v_or_b32_e32 v4, 2, v4
	v_cndmask_b32_e32 v11, v202, v11, vcc
	v_lshlrev_b32_e32 v150, 2, v11
	v_xor_b32_e32 v11, 4, v202
	v_cmp_lt_i32_e32 vcc, v11, v10
	v_lshlrev_b32_e32 v94, 2, v5
	v_lshlrev_b32_e64 v156, v4, 1
	v_cndmask_b32_e32 v11, v202, v11, vcc
	v_lshlrev_b32_e32 v151, 2, v11
	v_xor_b32_e32 v11, 8, v202
	v_cmp_lt_i32_e32 vcc, v11, v10
	v_lshlrev_b64 v[4:5], 12, v[8:9]
	v_or_b32_e32 v4, v4, v22
	v_cndmask_b32_e32 v11, v202, v11, vcc
	v_lshlrev_b32_e32 v152, 2, v11
	v_xor_b32_e32 v11, 16, v202
	v_cmp_lt_i32_e32 vcc, v11, v10
	v_lshl_add_u64 v[98:99], s[8:9], 0, v[6:7]
	v_lshl_add_u64 v[100:101], s[8:9], 0, v[4:5]
	v_cndmask_b32_e32 v11, v202, v11, vcc
	v_lshlrev_b32_e32 v153, 2, v11
	v_xor_b32_e32 v11, 32, v202
	v_cmp_lt_i32_e32 vcc, v11, v10
	s_mov_b64 s[22:23], 0
	s_nop 0
	v_cndmask_b32_e32 v10, v202, v11, vcc
	v_lshlrev_b32_e32 v154, 2, v10
	s_branch .LBB0_597
